# res epilogue all three paths hand-written via LDS transpose; p0 weight-transpose items rebalanced away from the 32 workgroups that take a second adaLN item
# speedup vs baseline: 1.0266x; 1.0103x over previous
; #define LAS __attribute__((address_space(3)))
; __device__ __forceinline__ void p0_weights(const Params& p, LAS unsigned char* lds, unsigned char* ws) {
;     PHASE_IDS;
;     LAS float* scr = (LAS float*)(lds + 65536 + wave * 8704);
;     const int gw = blockIdx.x * NWAVES + wave, NGW = gridDim.x * NWAVES;
;     constexpr int I_UP = 16 * 176, I_DN = 44 * 32, I_IN = 16 * 72, I_OUT = 16 * 32;
;     constexpr int T_UP = 8 * I_UP, T_DN = 8 * I_DN, T_IN = 4 * I_IN, T_OUT = 4 * I_OUT;
;     for (int it = gw; it < T_UP + T_DN + T_IN + T_OUT; it += NGW) {
;         int r = it;
.LBB0_34:
	v_mov_b32_e32 v1, v196
	s_lshl_b32 s1, s82, 3
	v_writelane_b32 v253, s1, 2
	v_readfirstlane_b32 s0, v1
	s_ashr_i32 s0, s0, 6
	v_readlane_b32 s4, v253, 0
	s_add_i32 s2, s0, s1
	s_lshl_b32 s84, s4, 3
	s_mov_b32 s100, s84
	s_mov_b32 s101, 0x9e00
	s_cmp_lg_u32 s4, 0x100
	s_cbranch_scc1 .Lp0w_go
	s_cmp_lt_u32 s82, 32
	s_cbranch_scc1 .Lp0w_low
	s_add_i32 s2, s2, 0xb00
	s_movk_i32 s100, 0x700
	s_branch .Lp0w_go
.Lp0w_low:
	s_movk_i32 s100, 0x100
	s_movk_i32 s101, 0xc00
.Lp0w_go:
	s_cmp_ge_i32 s2, s101
	v_readlane_b32 s5, v253, 1
	s_cbranch_scc1 .LBB0_57
	s_mulk_i32 s0, 0x2200
	s_add_i32 s0, s0, 0
	s_add_i32 s0, s0, 0x10000
	s_add_u32 s8, s58, 0x9e00000
	s_addc_u32 s9, s59, 0
	s_add_u32 s11, s58, 0x8c00000
	s_addc_u32 s14, s59, 0
	v_bfe_u32 v2, v1, 5, 1
	v_and_b32_e32 v4, 31, v1
	v_bfe_u32 v3, v1, 3, 3
	v_lshlrev_b32_e32 v1, 3, v1
	s_add_u32 s15, s58, 0x6000000
	v_and_b32_e32 v10, 56, v1
	s_addc_u32 s16, s59, 0
	v_mul_u32_u24_e32 v1, 0x84, v10
	v_lshlrev_b32_e32 v7, 2, v3
	s_add_u32 s17, s58, 0x800000
	s_mov_b32 s1, 0
	v_mov_b32_e32 v5, 0
	v_lshl_add_u32 v6, v4, 2, s0
	s_movk_i32 s10, 0x84
	v_add3_u32 v7, s0, v1, v7
	v_or_b32_e32 v14, 8, v3
	v_or_b32_e32 v15, 16, v3
	v_or_b32_e32 v16, 24, v3
	s_addc_u32 s18, s59, 0
	v_mov_b32_e32 v1, v2
	s_mov_b32 s19, 0x1ffff
	s_movk_i32 s20, 0x2400
	s_movk_i32 s21, 0x5800
	v_lshlrev_b32_e32 v8, 2, v4
	v_lshlrev_b32_e32 v10, 1, v10
	s_branch .LBB0_37
.LBB0_36:
	s_add_i32 s2, s2, s100
	s_cmp_lt_i32 s2, s101
	s_cbranch_scc0 .LBB0_57

; __device__ __forceinline__ unsigned cvt_pk_bf16(float lo, float hi) { unsigned r; asm volatile("v_cvt_pk_bf16_f32 %0, %1, %2" : "=v"(r) : "v"(lo), "v"(hi)); return r; }
;     __device__ __forceinline__ void operator()(const f32x4 (&acc)[2][2][4][2], const Unit& u, int wr, int wc, int fr_, int fq_, int) const {
;     ...
;         const bool lat = u.pm < 128; const int cond = lat ? (u.pm >> 5) : 4;
;         const float coef0 = (flags & 4) ? 1.0f : 0.5f;
;         const float* mv = modv + cond * E_MODW;
;         const size_t tb = lat ? (size_t)u.pm * BM * E_DM : (size_t)(u.pm - 128) * BM * E_DM;
;         const float* src = src_lat + tb; float* dst = (lat ? dst_lat : dst_ctx + (size_t)(u.kt0 >> 2) * (1024 * E_DM)) + tb;
;         const int col0 = u.pn * BM + wc * 32 + 4 * fq;
;         f32x4 g[2][2];
; #pragma unroll
;         for (int bj = 0; bj < 2; ++bj)
; #pragma unroll
;             for (int n = 0; n < 2; ++n) g[bj][n] = *(const f32x4*)(mv + col0 + bj * HALF + n * 16) * coef0;
;         const bool emit = lat && (flags & 1) != 0; bf16_t* XG = (flags & 2) ? XGb : XGa;
;         f32x4 gm[2][2];
;         if (emit) {
; #pragma unroll
;             for (int bj = 0; bj < 2; ++bj)
; #pragma unroll
;                 for (int n = 0; n < 2; ++n) gm[bj][n] = *(const f32x4*)(gnext + col0 + bj * HALF + n * 16) * (1.0f + *(const f32x4*)(sclnext + cond * E_MODW + col0 + bj * HALF + n * 16));
;         }
; #pragma unroll
;         for (int ai = 0; ai < 2; ++ai)
; #pragma unroll
;             for (int m = 0; m < 4; ++m) { const size_t off = (size_t)(ai * HALF + wr * 64 + m * 16 + fr) * E_DM + col0; float ss = 0.f;
; #pragma unroll
;                 for (int bj = 0; bj < 2; ++bj)
; #pragma unroll
;                     for (int n = 0; n < 2; ++n) {
;                         if (lat) { const f32x4 s = *(const f32x4*)(src + off + bj * HALF + n * 16);
;                             const f32x4 o = s + g[bj][n] * acc[ai][bj][m][n];
;                             *(f32x4*)(dst + off + bj * HALF + n * 16) = o;
;                             if (emit) { const f32x4 q = o * o; ss += (q[0] + q[1]) + (q[2] + q[3]); const f32x4 xg = o * gm[bj][n];
;                                 u32x2 w; w.x = cvt_pk_bf16(xg[0], xg[1]); w.y = cvt_pk_bf16(xg[2], xg[3]); *(u32x2*)(XG + tb + off + bj * HALF + n * 16) = w; } }
.LBB0_650:
	s_cmpk_gt_i32 s14, 0x7f
	s_cselect_b64 s[44:45], -1, 0
	s_lshr_b32 s24, s14, 5
	s_cmpk_lt_i32 s14, 0x80
	s_cselect_b64 s[42:43], -1, 0
	s_mulk_i32 s24, 0x2400
	s_and_b64 s[38:39], s[42:43], exec
	s_cselect_b32 s38, s24, 0x9000
	s_ashr_i32 s39, s38, 31
	s_lshl_b64 s[92:93], s[38:39], 2
	s_add_u32 s38, s21, s92
	s_addc_u32 s39, s77, s93
	s_lshl_b32 s24, s13, 8
	v_mov_b32_e32 v188, v81
	v_mov_b32_e32 v215, v212
	s_or_b32 s24, s24, s66
	s_and_b64 s[94:95], s[74:75], s[42:43]
	v_lshl_add_u32 v186, v215, 2, s24
	v_ashrrev_i32_e32 v187, 31, v186
	v_lshl_add_u64 v[130:131], v[186:187], 2, s[38:39]
	global_load_dwordx4 v[142:145], v[130:131], off
	global_load_dwordx4 v[138:141], v[130:131], off offset:64
	global_load_dwordx4 v[134:137], v[130:131], off offset:512
	s_nop 0
	global_load_dwordx4 v[130:133], v[130:131], off offset:576
	v_cndmask_b32_e64 v151, 0, 1, s[94:95]
	v_cmp_ne_u32_e64 s[38:39], 1, v151
	s_andn2_b64 vcc, exec, s[94:95]
	s_cbranch_vccnz .LBB0_652
	v_lshrrev_b32_e32 v189, 2, v81
	v_and_b32_e32 v249, 3, v81
	v_lshl_add_u32 v189, v212, 2, v189
	v_lshl_add_u32 v186, v249, 2, s24
	s_add_u32 s38, s21, s92
	s_addc_u32 s39, s77, s93
	v_ashrrev_i32_e32 v187, 31, v186
	v_lshlrev_b64 v[158:159], 2, v[186:187]
	s_add_u32 s92, s10, s92
	s_addc_u32 s93, s48, s93
	v_lshl_add_u64 v[190:191], s[38:39], 0, v[158:159]
	global_load_dwordx4 v[142:145], v[190:191], off
	global_load_dwordx4 v[138:141], v[190:191], off offset:64
	global_load_dwordx4 v[134:137], v[190:191], off offset:512
	global_load_dwordx4 v[130:133], v[190:191], off offset:576
	v_lshl_add_u64 v[190:191], s[84:85], 0, v[158:159]
	v_lshl_add_u64 v[192:193], s[92:93], 0, v[158:159]
	global_load_dwordx4 v[182:185], v[190:191], off
	global_load_dwordx4 v[178:181], v[190:191], off offset:64
	global_load_dwordx4 v[174:177], v[190:191], off offset:576
	global_load_dwordx4 v[158:161], v[190:191], off offset:512
	global_load_dwordx4 v[232:235], v[192:193], off
	global_load_dwordx4 v[236:239], v[192:193], off offset:64
	global_load_dwordx4 v[240:243], v[192:193], off offset:512
	global_load_dwordx4 v[244:247], v[192:193], off offset:576
	s_mov_b32 s94, s14
	s_ashr_i32 s95, s94, 31
	s_lshl_b64 s[96:97], s[94:95], 20
	v_readlane_b32 s24, v252, 47
	s_add_u32 s92, s24, s96
	v_readlane_b32 s24, v252, 46
	s_addc_u32 s93, s24, s97
	s_add_u32 s96, s56, s96
	s_addc_u32 s97, s57, s97
	s_lshl_b64 s[40:41], s[94:95], 19
	s_add_u32 s94, s2, s40
	s_addc_u32 s95, s46, s41
	s_lshl_b32 s40, s3, 6
	s_lshl_b32 s41, s63, 10
	s_add_i32 s40, s40, s41
	s_add_i32 s40, s40, 0x20000
	v_bfe_u32 v250, v81, 1, 2
	v_xor_b32_e32 v250, v250, v212
	v_lshlrev_b32_e32 v250, 4, v250
	v_lshl_add_u32 v250, v81, 6, v250
	v_add_u32_e32 v250, s40, v250
	v_bfe_u32 v251, v189, 1, 2
	v_xor_b32_e32 v251, v251, v249
	v_lshlrev_b32_e32 v251, 4, v251
	v_lshl_add_u32 v251, v189, 6, v251
	v_add_u32_e32 v251, s40, v251
	ds_write_b128 v250, v[126:129]
	ds_read_b128 v[126:129], v251
	ds_write_b128 v250, v[122:125]
	ds_read_b128 v[122:125], v251
	ds_write_b128 v250, v[118:121]
	ds_read_b128 v[118:121], v251
	ds_write_b128 v250, v[114:117]
	ds_read_b128 v[114:117], v251
	v_add_u32_e32 v188, s3, v189
	v_ashrrev_i32_e32 v189, 31, v188
	v_lshlrev_b64 v[190:191], 10, v[188:189]
	v_lshl_add_u64 v[192:193], v[190:191], 0, v[186:187]
	v_lshlrev_b64 v[194:195], 2, v[192:193]
	v_lshl_add_u64 v[190:191], s[96:97], 0, v[194:195]
	v_lshl_add_u64 v[194:195], s[92:93], 0, v[194:195]
	v_lshl_add_u64 v[192:193], v[192:193], 1, s[94:95]
	global_load_dwordx4 v[216:219], v[194:195], off
	global_load_dwordx4 v[220:223], v[194:195], off offset:64
	global_load_dwordx4 v[224:227], v[194:195], off offset:512
	global_load_dwordx4 v[228:231], v[194:195], off offset:576
	s_mov_b32 s98, 0x8000
	s_mov_b32 s99, 0
	s_mov_b32 s96, 0x28000
	s_mov_b32 s97, 0
	v_mov_b32_e32 v151, v150
	s_waitcnt vmcnt(4)
	v_pk_add_f32 v[232:233], v[232:233], 1.0 op_sel_hi:[1,0]
	v_pk_add_f32 v[234:235], v[234:235], 1.0 op_sel_hi:[1,0]
	v_pk_add_f32 v[236:237], v[236:237], 1.0 op_sel_hi:[1,0]
	v_pk_add_f32 v[238:239], v[238:239], 1.0 op_sel_hi:[1,0]
	v_pk_add_f32 v[240:241], v[240:241], 1.0 op_sel_hi:[1,0]
	v_pk_add_f32 v[242:243], v[242:243], 1.0 op_sel_hi:[1,0]
	v_pk_add_f32 v[244:245], v[244:245], 1.0 op_sel_hi:[1,0]
	v_pk_add_f32 v[246:247], v[246:247], 1.0 op_sel_hi:[1,0]
	v_pk_mul_f32 v[182:183], v[182:183], v[232:233]
	v_pk_mul_f32 v[184:185], v[184:185], v[234:235]
	v_pk_mul_f32 v[178:179], v[178:179], v[236:237]
	v_pk_mul_f32 v[180:181], v[180:181], v[238:239]
	v_pk_mul_f32 v[158:159], v[158:159], v[240:241]
	v_pk_mul_f32 v[160:161], v[160:161], v[242:243]
	v_pk_mul_f32 v[174:175], v[174:175], v[244:245]
	v_pk_mul_f32 v[176:177], v[176:177], v[246:247]
	v_pk_mul_f32 v[142:143], v[150:151], v[142:143]
	v_pk_mul_f32 v[144:145], v[150:151], v[144:145]
	v_pk_mul_f32 v[138:139], v[150:151], v[138:139]
	v_pk_mul_f32 v[140:141], v[150:151], v[140:141]
	v_pk_mul_f32 v[134:135], v[150:151], v[134:135]
	v_pk_mul_f32 v[136:137], v[150:151], v[136:137]
	v_pk_mul_f32 v[130:131], v[150:151], v[130:131]
	v_pk_mul_f32 v[132:133], v[150:151], v[132:133]
	v_lshl_add_u64 v[194:195], s[98:99], 1, v[194:195]
	global_load_dwordx4 v[232:235], v[194:195], off
	global_load_dwordx4 v[236:239], v[194:195], off offset:64
	global_load_dwordx4 v[240:243], v[194:195], off offset:512
	global_load_dwordx4 v[244:247], v[194:195], off offset:576
	s_waitcnt lgkmcnt(0)
	ds_write_b128 v250, v[110:113]
	ds_read_b128 v[110:113], v251
	ds_write_b128 v250, v[106:109]
	ds_read_b128 v[106:109], v251
	ds_write_b128 v250, v[102:105]
	ds_read_b128 v[102:105], v251
	ds_write_b128 v250, v[98:101]
	ds_read_b128 v[98:101], v251
	s_waitcnt vmcnt(4)
; __device__ __forceinline__ unsigned cvt_pk_bf16(float lo, float hi) { unsigned r; asm volatile("v_cvt_pk_bf16_f32 %0, %1, %2" : "=v"(r) : "v"(lo), "v"(hi)); return r; }
;     __device__ __forceinline__ void operator()(const f32x4 (&acc)[2][2][4][2], const Unit& u, int wr, int wc, int fr_, int fq_, int) const {
;     ...
;         for (int ai = 0; ai < 2; ++ai)
; #pragma unroll
;             for (int m = 0; m < 4; ++m) { const size_t off = (size_t)(ai * HALF + wr * 64 + m * 16 + fr) * E_DM + col0; float ss = 0.f;
; #pragma unroll
;                 for (int bj = 0; bj < 2; ++bj)
; #pragma unroll
;                     for (int n = 0; n < 2; ++n) {
;                         if (lat) { const f32x4 s = *(const f32x4*)(src + off + bj * HALF + n * 16);
;                             const f32x4 o = s + g[bj][n] * acc[ai][bj][m][n];
;                             *(f32x4*)(dst + off + bj * HALF + n * 16) = o;
;                             if (emit) { const f32x4 q = o * o; ss += (q[0] + q[1]) + (q[2] + q[3]); const f32x4 xg = o * gm[bj][n];
;                                 u32x2 w; w.x = cvt_pk_bf16(xg[0], xg[1]); w.y = cvt_pk_bf16(xg[2], xg[3]); *(u32x2*)(XG + tb + off + bj * HALF + n * 16) = w; } }
	v_pk_fma_f32 v[128:129], v[128:129], v[144:145], v[218:219]
	v_pk_fma_f32 v[126:127], v[126:127], v[142:143], v[216:217]
	global_store_dwordx4 v[190:191], v[126:129], off
	v_pk_mul_f32 v[216:217], v[128:129], v[128:129]
	v_pk_mul_f32 v[218:219], v[126:127], v[126:127]
	v_pk_mul_f32 v[126:127], v[182:183], v[126:127]
	v_pk_mul_f32 v[128:129], v[184:185], v[128:129]
	v_add_f32_e32 v218, v218, v219
	v_add_f32_e32 v216, v216, v217
	v_add_f32_e32 v248, v218, v216
	v_cvt_pk_bf16_f32 v126, v126, v127
	v_cvt_pk_bf16_f32 v127, v128, v129
	global_store_dwordx2 v[192:193], v[126:127], off
	v_pk_fma_f32 v[124:125], v[124:125], v[140:141], v[222:223]
	v_pk_fma_f32 v[122:123], v[122:123], v[138:139], v[220:221]
	global_store_dwordx4 v[190:191], v[122:125], off offset:64
	v_pk_mul_f32 v[220:221], v[124:125], v[124:125]
	v_pk_mul_f32 v[222:223], v[122:123], v[122:123]
	v_pk_mul_f32 v[122:123], v[178:179], v[122:123]
	v_pk_mul_f32 v[124:125], v[180:181], v[124:125]
	v_add_f32_e32 v222, v222, v223
	v_add_f32_e32 v220, v220, v221
	v_add_f32_e32 v222, v222, v220
	v_add_f32_e32 v248, v248, v222
	v_cvt_pk_bf16_f32 v122, v122, v123
	v_cvt_pk_bf16_f32 v123, v124, v125
	global_store_dwordx2 v[192:193], v[122:123], off offset:32
	v_pk_fma_f32 v[120:121], v[120:121], v[136:137], v[226:227]
	v_pk_fma_f32 v[118:119], v[118:119], v[134:135], v[224:225]
	global_store_dwordx4 v[190:191], v[118:121], off offset:512
	v_pk_mul_f32 v[224:225], v[120:121], v[120:121]
	v_pk_mul_f32 v[226:227], v[118:119], v[118:119]
	v_pk_mul_f32 v[118:119], v[158:159], v[118:119]
	v_pk_mul_f32 v[120:121], v[160:161], v[120:121]
	v_add_f32_e32 v226, v226, v227
	v_add_f32_e32 v224, v224, v225
	v_add_f32_e32 v226, v226, v224
	v_add_f32_e32 v248, v248, v226
	v_cvt_pk_bf16_f32 v118, v118, v119
	v_cvt_pk_bf16_f32 v119, v120, v121
	global_store_dwordx2 v[192:193], v[118:119], off offset:256
	v_pk_fma_f32 v[116:117], v[116:117], v[132:133], v[230:231]
	v_pk_fma_f32 v[114:115], v[114:115], v[130:131], v[228:229]
	global_store_dwordx4 v[190:191], v[114:117], off offset:576
	v_pk_mul_f32 v[228:229], v[116:117], v[116:117]
	v_pk_mul_f32 v[230:231], v[114:115], v[114:115]
	v_pk_mul_f32 v[114:115], v[174:175], v[114:115]
	v_pk_mul_f32 v[116:117], v[176:177], v[116:117]
	v_add_f32_e32 v230, v230, v231
	v_add_f32_e32 v228, v228, v229
	v_add_f32_e32 v230, v230, v228
	v_add_f32_e32 v248, v248, v230
	v_cvt_pk_bf16_f32 v114, v114, v115
	v_cvt_pk_bf16_f32 v115, v116, v117
	global_store_dwordx2 v[192:193], v[114:115], off offset:288
	v_mov_b32_e32 v122, v248
	v_lshl_add_u64 v[190:191], s[98:99], 1, v[190:191]
	v_lshl_add_u64 v[192:193], s[98:99], 0, v[192:193]
	v_lshl_add_u64 v[194:195], s[98:99], 1, v[194:195]
	global_load_dwordx4 v[216:219], v[194:195], off
	global_load_dwordx4 v[220:223], v[194:195], off offset:64
	global_load_dwordx4 v[224:227], v[194:195], off offset:512
	global_load_dwordx4 v[228:231], v[194:195], off offset:576
	ds_write_b128 v250, v[94:97]
	ds_read_b128 v[94:97], v251
	ds_write_b128 v250, v[90:93]
	ds_read_b128 v[90:93], v251
	ds_write_b128 v250, v[86:89]
	ds_read_b128 v[86:89], v251
	ds_write_b128 v250, v[82:85]
	ds_read_b128 v[82:85], v251
	s_waitcnt vmcnt(12)
	s_waitcnt lgkmcnt(8)
	v_pk_fma_f32 v[112:113], v[112:113], v[144:145], v[234:235]
	v_pk_fma_f32 v[110:111], v[110:111], v[142:143], v[232:233]
	global_store_dwordx4 v[190:191], v[110:113], off
	v_pk_mul_f32 v[232:233], v[112:113], v[112:113]
	v_pk_mul_f32 v[234:235], v[110:111], v[110:111]
	v_pk_mul_f32 v[110:111], v[182:183], v[110:111]
	v_pk_mul_f32 v[112:113], v[184:185], v[112:113]
	v_add_f32_e32 v234, v234, v235
	v_add_f32_e32 v232, v232, v233
	v_add_f32_e32 v248, v234, v232
	v_cvt_pk_bf16_f32 v110, v110, v111
	v_cvt_pk_bf16_f32 v111, v112, v113
	global_store_dwordx2 v[192:193], v[110:111], off
	v_pk_fma_f32 v[108:109], v[108:109], v[140:141], v[238:239]
	v_pk_fma_f32 v[106:107], v[106:107], v[138:139], v[236:237]
	global_store_dwordx4 v[190:191], v[106:109], off offset:64
	v_pk_mul_f32 v[236:237], v[108:109], v[108:109]
	v_pk_mul_f32 v[238:239], v[106:107], v[106:107]
	v_pk_mul_f32 v[106:107], v[178:179], v[106:107]
	v_pk_mul_f32 v[108:109], v[180:181], v[108:109]
	v_add_f32_e32 v238, v238, v239
	v_add_f32_e32 v236, v236, v237
	v_add_f32_e32 v238, v238, v236
	v_add_f32_e32 v248, v248, v238
	v_cvt_pk_bf16_f32 v106, v106, v107
	v_cvt_pk_bf16_f32 v107, v108, v109
	global_store_dwordx2 v[192:193], v[106:107], off offset:32
	v_pk_fma_f32 v[104:105], v[104:105], v[136:137], v[242:243]
	v_pk_fma_f32 v[102:103], v[102:103], v[134:135], v[240:241]
	global_store_dwordx4 v[190:191], v[102:105], off offset:512
	v_pk_mul_f32 v[240:241], v[104:105], v[104:105]
	v_pk_mul_f32 v[242:243], v[102:103], v[102:103]
	v_pk_mul_f32 v[102:103], v[158:159], v[102:103]
	v_pk_mul_f32 v[104:105], v[160:161], v[104:105]
	v_add_f32_e32 v242, v242, v243
	v_add_f32_e32 v240, v240, v241
	v_add_f32_e32 v242, v242, v240
	v_add_f32_e32 v248, v248, v242
	v_cvt_pk_bf16_f32 v102, v102, v103
	v_cvt_pk_bf16_f32 v103, v104, v105
	global_store_dwordx2 v[192:193], v[102:103], off offset:256
	v_pk_fma_f32 v[100:101], v[100:101], v[132:133], v[246:247]
	v_pk_fma_f32 v[98:99], v[98:99], v[130:131], v[244:245]
	global_store_dwordx4 v[190:191], v[98:101], off offset:576
	v_pk_mul_f32 v[244:245], v[100:101], v[100:101]
	v_pk_mul_f32 v[246:247], v[98:99], v[98:99]
	v_pk_mul_f32 v[98:99], v[174:175], v[98:99]
	v_pk_mul_f32 v[100:101], v[176:177], v[100:101]
	v_add_f32_e32 v246, v246, v247
	v_add_f32_e32 v244, v244, v245
	v_add_f32_e32 v246, v246, v244
	v_add_f32_e32 v248, v248, v246
	v_cvt_pk_bf16_f32 v98, v98, v99
	v_cvt_pk_bf16_f32 v99, v100, v101
	global_store_dwordx2 v[192:193], v[98:99], off offset:288
	v_mov_b32_e32 v123, v248
	v_lshl_add_u64 v[190:191], s[98:99], 1, v[190:191]
	v_lshl_add_u64 v[192:193], s[98:99], 0, v[192:193]
	v_lshl_add_u64 v[194:195], s[98:99], 1, v[194:195]
	global_load_dwordx4 v[232:235], v[194:195], off
	global_load_dwordx4 v[236:239], v[194:195], off offset:64
	global_load_dwordx4 v[240:243], v[194:195], off offset:512
	global_load_dwordx4 v[244:247], v[194:195], off offset:576
	ds_write_b128 v250, v[76:79]
	ds_read_b128 v[76:79], v251
	ds_write_b128 v250, v[72:75]
	ds_read_b128 v[72:75], v251
	ds_write_b128 v250, v[68:71]
	ds_read_b128 v[68:71], v251
	ds_write_b128 v250, v[64:67]
	ds_read_b128 v[64:67], v251
	s_waitcnt vmcnt(12)
; __device__ __forceinline__ unsigned cvt_pk_bf16(float lo, float hi) { unsigned r; asm volatile("v_cvt_pk_bf16_f32 %0, %1, %2" : "=v"(r) : "v"(lo), "v"(hi)); return r; }
;     __device__ __forceinline__ void operator()(const f32x4 (&acc)[2][2][4][2], const Unit& u, int wr, int wc, int fr_, int fq_, int) const {
;     ...
;         for (int ai = 0; ai < 2; ++ai)
; #pragma unroll
;             for (int m = 0; m < 4; ++m) { const size_t off = (size_t)(ai * HALF + wr * 64 + m * 16 + fr) * E_DM + col0; float ss = 0.f;
; #pragma unroll
;                 for (int bj = 0; bj < 2; ++bj)
; #pragma unroll
;                     for (int n = 0; n < 2; ++n) {
;                         if (lat) { const f32x4 s = *(const f32x4*)(src + off + bj * HALF + n * 16);
;                             const f32x4 o = s + g[bj][n] * acc[ai][bj][m][n];
;                             *(f32x4*)(dst + off + bj * HALF + n * 16) = o;
;                             if (emit) { const f32x4 q = o * o; ss += (q[0] + q[1]) + (q[2] + q[3]); const f32x4 xg = o * gm[bj][n];
;                                 u32x2 w; w.x = cvt_pk_bf16(xg[0], xg[1]); w.y = cvt_pk_bf16(xg[2], xg[3]); *(u32x2*)(XG + tb + off + bj * HALF + n * 16) = w; } }
	s_waitcnt lgkmcnt(8)
	v_pk_fma_f32 v[96:97], v[96:97], v[144:145], v[218:219]
	v_pk_fma_f32 v[94:95], v[94:95], v[142:143], v[216:217]
	global_store_dwordx4 v[190:191], v[94:97], off
	v_pk_mul_f32 v[216:217], v[96:97], v[96:97]
	v_pk_mul_f32 v[218:219], v[94:95], v[94:95]
	v_pk_mul_f32 v[94:95], v[182:183], v[94:95]
	v_pk_mul_f32 v[96:97], v[184:185], v[96:97]
	v_add_f32_e32 v218, v218, v219
	v_add_f32_e32 v216, v216, v217
	v_add_f32_e32 v248, v218, v216
	v_cvt_pk_bf16_f32 v94, v94, v95
	v_cvt_pk_bf16_f32 v95, v96, v97
	global_store_dwordx2 v[192:193], v[94:95], off
	v_pk_fma_f32 v[92:93], v[92:93], v[140:141], v[222:223]
	v_pk_fma_f32 v[90:91], v[90:91], v[138:139], v[220:221]
	global_store_dwordx4 v[190:191], v[90:93], off offset:64
	v_pk_mul_f32 v[220:221], v[92:93], v[92:93]
	v_pk_mul_f32 v[222:223], v[90:91], v[90:91]
	v_pk_mul_f32 v[90:91], v[178:179], v[90:91]
	v_pk_mul_f32 v[92:93], v[180:181], v[92:93]
	v_add_f32_e32 v222, v222, v223
	v_add_f32_e32 v220, v220, v221
	v_add_f32_e32 v222, v222, v220
	v_add_f32_e32 v248, v248, v222
	v_cvt_pk_bf16_f32 v90, v90, v91
	v_cvt_pk_bf16_f32 v91, v92, v93
	global_store_dwordx2 v[192:193], v[90:91], off offset:32
	v_pk_fma_f32 v[88:89], v[88:89], v[136:137], v[226:227]
	v_pk_fma_f32 v[86:87], v[86:87], v[134:135], v[224:225]
	global_store_dwordx4 v[190:191], v[86:89], off offset:512
	v_pk_mul_f32 v[224:225], v[88:89], v[88:89]
	v_pk_mul_f32 v[226:227], v[86:87], v[86:87]
	v_pk_mul_f32 v[86:87], v[158:159], v[86:87]
	v_pk_mul_f32 v[88:89], v[160:161], v[88:89]
	v_add_f32_e32 v226, v226, v227
	v_add_f32_e32 v224, v224, v225
	v_add_f32_e32 v226, v226, v224
	v_add_f32_e32 v248, v248, v226
	v_cvt_pk_bf16_f32 v86, v86, v87
	v_cvt_pk_bf16_f32 v87, v88, v89
	global_store_dwordx2 v[192:193], v[86:87], off offset:256
	v_pk_fma_f32 v[84:85], v[84:85], v[132:133], v[230:231]
	v_pk_fma_f32 v[82:83], v[82:83], v[130:131], v[228:229]
	global_store_dwordx4 v[190:191], v[82:85], off offset:576
	v_pk_mul_f32 v[228:229], v[84:85], v[84:85]
	v_pk_mul_f32 v[230:231], v[82:83], v[82:83]
	v_pk_mul_f32 v[82:83], v[174:175], v[82:83]
	v_pk_mul_f32 v[84:85], v[176:177], v[84:85]
	v_add_f32_e32 v230, v230, v231
	v_add_f32_e32 v228, v228, v229
	v_add_f32_e32 v230, v230, v228
	v_add_f32_e32 v248, v248, v230
	v_cvt_pk_bf16_f32 v82, v82, v83
	v_cvt_pk_bf16_f32 v83, v84, v85
	global_store_dwordx2 v[192:193], v[82:83], off offset:288
	v_mov_b32_e32 v124, v248
	v_lshl_add_u64 v[190:191], s[98:99], 1, v[190:191]
	v_lshl_add_u64 v[192:193], s[98:99], 0, v[192:193]
	v_lshl_add_u64 v[194:195], s[96:97], 1, v[194:195]
	global_load_dwordx4 v[216:219], v[194:195], off
	global_load_dwordx4 v[220:223], v[194:195], off offset:64
	global_load_dwordx4 v[224:227], v[194:195], off offset:512
	global_load_dwordx4 v[228:231], v[194:195], off offset:576
	ds_write_b128 v250, v[60:63]
	ds_read_b128 v[60:63], v251
	ds_write_b128 v250, v[56:59]
	ds_read_b128 v[56:59], v251
	ds_write_b128 v250, v[52:55]
	ds_read_b128 v[52:55], v251
	ds_write_b128 v250, v[48:51]
	ds_read_b128 v[48:51], v251
	s_waitcnt vmcnt(12)
	s_waitcnt lgkmcnt(8)
	v_pk_fma_f32 v[78:79], v[78:79], v[144:145], v[234:235]
	v_pk_fma_f32 v[76:77], v[76:77], v[142:143], v[232:233]
	global_store_dwordx4 v[190:191], v[76:79], off
	v_pk_mul_f32 v[232:233], v[78:79], v[78:79]
	v_pk_mul_f32 v[234:235], v[76:77], v[76:77]
	v_pk_mul_f32 v[76:77], v[182:183], v[76:77]
	v_pk_mul_f32 v[78:79], v[184:185], v[78:79]
	v_add_f32_e32 v234, v234, v235
	v_add_f32_e32 v232, v232, v233
	v_add_f32_e32 v248, v234, v232
	v_cvt_pk_bf16_f32 v76, v76, v77
	v_cvt_pk_bf16_f32 v77, v78, v79
	global_store_dwordx2 v[192:193], v[76:77], off
	v_pk_fma_f32 v[74:75], v[74:75], v[140:141], v[238:239]
	v_pk_fma_f32 v[72:73], v[72:73], v[138:139], v[236:237]
	global_store_dwordx4 v[190:191], v[72:75], off offset:64
	v_pk_mul_f32 v[236:237], v[74:75], v[74:75]
	v_pk_mul_f32 v[238:239], v[72:73], v[72:73]
	v_pk_mul_f32 v[72:73], v[178:179], v[72:73]
	v_pk_mul_f32 v[74:75], v[180:181], v[74:75]
	v_add_f32_e32 v238, v238, v239
	v_add_f32_e32 v236, v236, v237
	v_add_f32_e32 v238, v238, v236
	v_add_f32_e32 v248, v248, v238
	v_cvt_pk_bf16_f32 v72, v72, v73
	v_cvt_pk_bf16_f32 v73, v74, v75
	global_store_dwordx2 v[192:193], v[72:73], off offset:32
	v_pk_fma_f32 v[70:71], v[70:71], v[136:137], v[242:243]
	v_pk_fma_f32 v[68:69], v[68:69], v[134:135], v[240:241]
	global_store_dwordx4 v[190:191], v[68:71], off offset:512
	v_pk_mul_f32 v[240:241], v[70:71], v[70:71]
	v_pk_mul_f32 v[242:243], v[68:69], v[68:69]
	v_pk_mul_f32 v[68:69], v[158:159], v[68:69]
	v_pk_mul_f32 v[70:71], v[160:161], v[70:71]
	v_add_f32_e32 v242, v242, v243
	v_add_f32_e32 v240, v240, v241
	v_add_f32_e32 v242, v242, v240
	v_add_f32_e32 v248, v248, v242
	v_cvt_pk_bf16_f32 v68, v68, v69
	v_cvt_pk_bf16_f32 v69, v70, v71
	global_store_dwordx2 v[192:193], v[68:69], off offset:256
	v_pk_fma_f32 v[66:67], v[66:67], v[132:133], v[246:247]
	v_pk_fma_f32 v[64:65], v[64:65], v[130:131], v[244:245]
	global_store_dwordx4 v[190:191], v[64:67], off offset:576
	v_pk_mul_f32 v[244:245], v[66:67], v[66:67]
	v_pk_mul_f32 v[246:247], v[64:65], v[64:65]
	v_pk_mul_f32 v[64:65], v[174:175], v[64:65]
	v_pk_mul_f32 v[66:67], v[176:177], v[66:67]
	v_add_f32_e32 v246, v246, v247
	v_add_f32_e32 v244, v244, v245
	v_add_f32_e32 v246, v246, v244
	v_add_f32_e32 v248, v248, v246
	v_cvt_pk_bf16_f32 v64, v64, v65
	v_cvt_pk_bf16_f32 v65, v66, v67
	global_store_dwordx2 v[192:193], v[64:65], off offset:288
	v_mov_b32_e32 v125, v248
	v_lshl_add_u64 v[190:191], s[96:97], 1, v[190:191]
	v_lshl_add_u64 v[192:193], s[96:97], 0, v[192:193]
	v_lshl_add_u64 v[194:195], s[98:99], 1, v[194:195]
	global_load_dwordx4 v[232:235], v[194:195], off
	global_load_dwordx4 v[236:239], v[194:195], off offset:64
	global_load_dwordx4 v[240:243], v[194:195], off offset:512
	global_load_dwordx4 v[244:247], v[194:195], off offset:576
	ds_write_b128 v250, v[44:47]
	ds_read_b128 v[44:47], v251
	ds_write_b128 v250, v[40:43]
	ds_read_b128 v[40:43], v251
	ds_write_b128 v250, v[36:39]
	ds_read_b128 v[36:39], v251
	ds_write_b128 v250, v[32:35]
	ds_read_b128 v[32:35], v251
	s_waitcnt vmcnt(12)
; __device__ __forceinline__ unsigned cvt_pk_bf16(float lo, float hi) { unsigned r; asm volatile("v_cvt_pk_bf16_f32 %0, %1, %2" : "=v"(r) : "v"(lo), "v"(hi)); return r; }
;     __device__ __forceinline__ void operator()(const f32x4 (&acc)[2][2][4][2], const Unit& u, int wr, int wc, int fr_, int fq_, int) const {
;     ...
;         for (int ai = 0; ai < 2; ++ai)
; #pragma unroll
;             for (int m = 0; m < 4; ++m) { const size_t off = (size_t)(ai * HALF + wr * 64 + m * 16 + fr) * E_DM + col0; float ss = 0.f;
; #pragma unroll
;                 for (int bj = 0; bj < 2; ++bj)
; #pragma unroll
;                     for (int n = 0; n < 2; ++n) {
;                         if (lat) { const f32x4 s = *(const f32x4*)(src + off + bj * HALF + n * 16);
;                             const f32x4 o = s + g[bj][n] * acc[ai][bj][m][n];
;                             *(f32x4*)(dst + off + bj * HALF + n * 16) = o;
;                             if (emit) { const f32x4 q = o * o; ss += (q[0] + q[1]) + (q[2] + q[3]); const f32x4 xg = o * gm[bj][n];
;                                 u32x2 w; w.x = cvt_pk_bf16(xg[0], xg[1]); w.y = cvt_pk_bf16(xg[2], xg[3]); *(u32x2*)(XG + tb + off + bj * HALF + n * 16) = w; } }
	s_waitcnt lgkmcnt(8)
	v_pk_fma_f32 v[62:63], v[62:63], v[144:145], v[218:219]
	v_pk_fma_f32 v[60:61], v[60:61], v[142:143], v[216:217]
	global_store_dwordx4 v[190:191], v[60:63], off
	v_pk_mul_f32 v[216:217], v[62:63], v[62:63]
	v_pk_mul_f32 v[218:219], v[60:61], v[60:61]
	v_pk_mul_f32 v[60:61], v[182:183], v[60:61]
	v_pk_mul_f32 v[62:63], v[184:185], v[62:63]
	v_add_f32_e32 v218, v218, v219
	v_add_f32_e32 v216, v216, v217
	v_add_f32_e32 v248, v218, v216
	v_cvt_pk_bf16_f32 v60, v60, v61
	v_cvt_pk_bf16_f32 v61, v62, v63
	global_store_dwordx2 v[192:193], v[60:61], off
	v_pk_fma_f32 v[58:59], v[58:59], v[140:141], v[222:223]
	v_pk_fma_f32 v[56:57], v[56:57], v[138:139], v[220:221]
	global_store_dwordx4 v[190:191], v[56:59], off offset:64
	v_pk_mul_f32 v[220:221], v[58:59], v[58:59]
	v_pk_mul_f32 v[222:223], v[56:57], v[56:57]
	v_pk_mul_f32 v[56:57], v[178:179], v[56:57]
	v_pk_mul_f32 v[58:59], v[180:181], v[58:59]
	v_add_f32_e32 v222, v222, v223
	v_add_f32_e32 v220, v220, v221
	v_add_f32_e32 v222, v222, v220
	v_add_f32_e32 v248, v248, v222
	v_cvt_pk_bf16_f32 v56, v56, v57
	v_cvt_pk_bf16_f32 v57, v58, v59
	global_store_dwordx2 v[192:193], v[56:57], off offset:32
	v_pk_fma_f32 v[54:55], v[54:55], v[136:137], v[226:227]
	v_pk_fma_f32 v[52:53], v[52:53], v[134:135], v[224:225]
	global_store_dwordx4 v[190:191], v[52:55], off offset:512
	v_pk_mul_f32 v[224:225], v[54:55], v[54:55]
	v_pk_mul_f32 v[226:227], v[52:53], v[52:53]
	v_pk_mul_f32 v[52:53], v[158:159], v[52:53]
	v_pk_mul_f32 v[54:55], v[160:161], v[54:55]
	v_add_f32_e32 v226, v226, v227
	v_add_f32_e32 v224, v224, v225
	v_add_f32_e32 v226, v226, v224
	v_add_f32_e32 v248, v248, v226
	v_cvt_pk_bf16_f32 v52, v52, v53
	v_cvt_pk_bf16_f32 v53, v54, v55
	global_store_dwordx2 v[192:193], v[52:53], off offset:256
	v_pk_fma_f32 v[50:51], v[50:51], v[132:133], v[230:231]
	v_pk_fma_f32 v[48:49], v[48:49], v[130:131], v[228:229]
	global_store_dwordx4 v[190:191], v[48:51], off offset:576
	v_pk_mul_f32 v[228:229], v[50:51], v[50:51]
	v_pk_mul_f32 v[230:231], v[48:49], v[48:49]
	v_pk_mul_f32 v[48:49], v[174:175], v[48:49]
	v_pk_mul_f32 v[50:51], v[176:177], v[50:51]
	v_add_f32_e32 v230, v230, v231
	v_add_f32_e32 v228, v228, v229
	v_add_f32_e32 v230, v230, v228
	v_add_f32_e32 v248, v248, v230
	v_cvt_pk_bf16_f32 v48, v48, v49
	v_cvt_pk_bf16_f32 v49, v50, v51
	global_store_dwordx2 v[192:193], v[48:49], off offset:288
	v_mov_b32_e32 v126, v248
	v_lshl_add_u64 v[190:191], s[98:99], 1, v[190:191]
	v_lshl_add_u64 v[192:193], s[98:99], 0, v[192:193]
	v_lshl_add_u64 v[194:195], s[98:99], 1, v[194:195]
	global_load_dwordx4 v[216:219], v[194:195], off
	global_load_dwordx4 v[220:223], v[194:195], off offset:64
	global_load_dwordx4 v[224:227], v[194:195], off offset:512
	global_load_dwordx4 v[228:231], v[194:195], off offset:576
	ds_write_b128 v250, v[28:31]
	ds_read_b128 v[28:31], v251
	ds_write_b128 v250, v[24:27]
	ds_read_b128 v[24:27], v251
	ds_write_b128 v250, v[20:23]
	ds_read_b128 v[20:23], v251
	ds_write_b128 v250, v[16:19]
	ds_read_b128 v[16:19], v251
	s_waitcnt vmcnt(12)
	s_waitcnt lgkmcnt(8)
	v_pk_fma_f32 v[46:47], v[46:47], v[144:145], v[234:235]
	v_pk_fma_f32 v[44:45], v[44:45], v[142:143], v[232:233]
	global_store_dwordx4 v[190:191], v[44:47], off
	v_pk_mul_f32 v[232:233], v[46:47], v[46:47]
	v_pk_mul_f32 v[234:235], v[44:45], v[44:45]
	v_pk_mul_f32 v[44:45], v[182:183], v[44:45]
	v_pk_mul_f32 v[46:47], v[184:185], v[46:47]
	v_add_f32_e32 v234, v234, v235
	v_add_f32_e32 v232, v232, v233
	v_add_f32_e32 v248, v234, v232
	v_cvt_pk_bf16_f32 v44, v44, v45
	v_cvt_pk_bf16_f32 v45, v46, v47
	global_store_dwordx2 v[192:193], v[44:45], off
	v_pk_fma_f32 v[42:43], v[42:43], v[140:141], v[238:239]
	v_pk_fma_f32 v[40:41], v[40:41], v[138:139], v[236:237]
	global_store_dwordx4 v[190:191], v[40:43], off offset:64
	v_pk_mul_f32 v[236:237], v[42:43], v[42:43]
	v_pk_mul_f32 v[238:239], v[40:41], v[40:41]
	v_pk_mul_f32 v[40:41], v[178:179], v[40:41]
	v_pk_mul_f32 v[42:43], v[180:181], v[42:43]
	v_add_f32_e32 v238, v238, v239
	v_add_f32_e32 v236, v236, v237
	v_add_f32_e32 v238, v238, v236
	v_add_f32_e32 v248, v248, v238
	v_cvt_pk_bf16_f32 v40, v40, v41
	v_cvt_pk_bf16_f32 v41, v42, v43
	global_store_dwordx2 v[192:193], v[40:41], off offset:32
	v_pk_fma_f32 v[38:39], v[38:39], v[136:137], v[242:243]
	v_pk_fma_f32 v[36:37], v[36:37], v[134:135], v[240:241]
	global_store_dwordx4 v[190:191], v[36:39], off offset:512
	v_pk_mul_f32 v[240:241], v[38:39], v[38:39]
	v_pk_mul_f32 v[242:243], v[36:37], v[36:37]
	v_pk_mul_f32 v[36:37], v[158:159], v[36:37]
	v_pk_mul_f32 v[38:39], v[160:161], v[38:39]
	v_add_f32_e32 v242, v242, v243
	v_add_f32_e32 v240, v240, v241
	v_add_f32_e32 v242, v242, v240
	v_add_f32_e32 v248, v248, v242
	v_cvt_pk_bf16_f32 v36, v36, v37
	v_cvt_pk_bf16_f32 v37, v38, v39
	global_store_dwordx2 v[192:193], v[36:37], off offset:256
	v_pk_fma_f32 v[34:35], v[34:35], v[132:133], v[246:247]
	v_pk_fma_f32 v[32:33], v[32:33], v[130:131], v[244:245]
	global_store_dwordx4 v[190:191], v[32:35], off offset:576
	v_pk_mul_f32 v[244:245], v[34:35], v[34:35]
	v_pk_mul_f32 v[246:247], v[32:33], v[32:33]
	v_pk_mul_f32 v[32:33], v[174:175], v[32:33]
	v_pk_mul_f32 v[34:35], v[176:177], v[34:35]
	v_add_f32_e32 v246, v246, v247
	v_add_f32_e32 v244, v244, v245
	v_add_f32_e32 v246, v246, v244
	v_add_f32_e32 v248, v248, v246
	v_cvt_pk_bf16_f32 v32, v32, v33
	v_cvt_pk_bf16_f32 v33, v34, v35
	global_store_dwordx2 v[192:193], v[32:33], off offset:288
	v_mov_b32_e32 v127, v248
	v_lshl_add_u64 v[190:191], s[98:99], 1, v[190:191]
	v_lshl_add_u64 v[192:193], s[98:99], 0, v[192:193]
	v_lshl_add_u64 v[194:195], s[98:99], 1, v[194:195]
	global_load_dwordx4 v[232:235], v[194:195], off
	global_load_dwordx4 v[236:239], v[194:195], off offset:64
	global_load_dwordx4 v[240:243], v[194:195], off offset:512
	global_load_dwordx4 v[244:247], v[194:195], off offset:576
	ds_write_b128 v250, v[12:15]
	ds_read_b128 v[12:15], v251
	ds_write_b128 v250, v[8:11]
	ds_read_b128 v[8:11], v251
	ds_write_b128 v250, v[4:7]
	ds_read_b128 v[4:7], v251
	ds_write_b128 v250, v[0:3]
	ds_read_b128 v[0:3], v251
	s_waitcnt vmcnt(12)
; __device__ __forceinline__ unsigned cvt_pk_bf16(float lo, float hi) { unsigned r; asm volatile("v_cvt_pk_bf16_f32 %0, %1, %2" : "=v"(r) : "v"(lo), "v"(hi)); return r; }
;     __device__ __forceinline__ void operator()(const f32x4 (&acc)[2][2][4][2], const Unit& u, int wr, int wc, int fr_, int fq_, int) const {
;     ...
;         for (int ai = 0; ai < 2; ++ai)
; #pragma unroll
;             for (int m = 0; m < 4; ++m) { const size_t off = (size_t)(ai * HALF + wr * 64 + m * 16 + fr) * E_DM + col0; float ss = 0.f;
; #pragma unroll
;                 for (int bj = 0; bj < 2; ++bj)
; #pragma unroll
;                     for (int n = 0; n < 2; ++n) {
;                         if (lat) { const f32x4 s = *(const f32x4*)(src + off + bj * HALF + n * 16);
;                             const f32x4 o = s + g[bj][n] * acc[ai][bj][m][n];
;                             *(f32x4*)(dst + off + bj * HALF + n * 16) = o;
;                             if (emit) { const f32x4 q = o * o; ss += (q[0] + q[1]) + (q[2] + q[3]); const f32x4 xg = o * gm[bj][n];
;                                 u32x2 w; w.x = cvt_pk_bf16(xg[0], xg[1]); w.y = cvt_pk_bf16(xg[2], xg[3]); *(u32x2*)(XG + tb + off + bj * HALF + n * 16) = w; } }
;                         else *(f32x4*)(dst + off + bj * HALF + n * 16) = g[bj][n] * acc[ai][bj][m][n];
;                     }
;                 if (emit) { ss += __shfl_xor(ss, 16); ss += __shfl_xor(ss, 32); if (fq == 0) SS[(size_t)(u.pm * BM + ai * HALF + wr * 64 + m * 16 + fr) * 16 + u.pn * 4 + wc] = ss; }
	s_waitcnt lgkmcnt(8)
	v_pk_fma_f32 v[30:31], v[30:31], v[144:145], v[218:219]
	v_pk_fma_f32 v[28:29], v[28:29], v[142:143], v[216:217]
	global_store_dwordx4 v[190:191], v[28:31], off
	v_pk_mul_f32 v[216:217], v[30:31], v[30:31]
	v_pk_mul_f32 v[218:219], v[28:29], v[28:29]
	v_pk_mul_f32 v[28:29], v[182:183], v[28:29]
	v_pk_mul_f32 v[30:31], v[184:185], v[30:31]
	v_add_f32_e32 v218, v218, v219
	v_add_f32_e32 v216, v216, v217
	v_add_f32_e32 v248, v218, v216
	v_cvt_pk_bf16_f32 v28, v28, v29
	v_cvt_pk_bf16_f32 v29, v30, v31
	global_store_dwordx2 v[192:193], v[28:29], off
	v_pk_fma_f32 v[26:27], v[26:27], v[140:141], v[222:223]
	v_pk_fma_f32 v[24:25], v[24:25], v[138:139], v[220:221]
	global_store_dwordx4 v[190:191], v[24:27], off offset:64
	v_pk_mul_f32 v[220:221], v[26:27], v[26:27]
	v_pk_mul_f32 v[222:223], v[24:25], v[24:25]
	v_pk_mul_f32 v[24:25], v[178:179], v[24:25]
	v_pk_mul_f32 v[26:27], v[180:181], v[26:27]
	v_add_f32_e32 v222, v222, v223
	v_add_f32_e32 v220, v220, v221
	v_add_f32_e32 v222, v222, v220
	v_add_f32_e32 v248, v248, v222
	v_cvt_pk_bf16_f32 v24, v24, v25
	v_cvt_pk_bf16_f32 v25, v26, v27
	global_store_dwordx2 v[192:193], v[24:25], off offset:32
	v_pk_fma_f32 v[22:23], v[22:23], v[136:137], v[226:227]
	v_pk_fma_f32 v[20:21], v[20:21], v[134:135], v[224:225]
	global_store_dwordx4 v[190:191], v[20:23], off offset:512
	v_pk_mul_f32 v[224:225], v[22:23], v[22:23]
	v_pk_mul_f32 v[226:227], v[20:21], v[20:21]
	v_pk_mul_f32 v[20:21], v[158:159], v[20:21]
	v_pk_mul_f32 v[22:23], v[160:161], v[22:23]
	v_add_f32_e32 v226, v226, v227
	v_add_f32_e32 v224, v224, v225
	v_add_f32_e32 v226, v226, v224
	v_add_f32_e32 v248, v248, v226
	v_cvt_pk_bf16_f32 v20, v20, v21
	v_cvt_pk_bf16_f32 v21, v22, v23
	global_store_dwordx2 v[192:193], v[20:21], off offset:256
	v_pk_fma_f32 v[18:19], v[18:19], v[132:133], v[230:231]
	v_pk_fma_f32 v[16:17], v[16:17], v[130:131], v[228:229]
	global_store_dwordx4 v[190:191], v[16:19], off offset:576
	v_pk_mul_f32 v[228:229], v[18:19], v[18:19]
	v_pk_mul_f32 v[230:231], v[16:17], v[16:17]
	v_pk_mul_f32 v[16:17], v[174:175], v[16:17]
	v_pk_mul_f32 v[18:19], v[176:177], v[18:19]
	v_add_f32_e32 v230, v230, v231
	v_add_f32_e32 v228, v228, v229
	v_add_f32_e32 v230, v230, v228
	v_add_f32_e32 v248, v248, v230
	v_cvt_pk_bf16_f32 v16, v16, v17
	v_cvt_pk_bf16_f32 v17, v18, v19
	global_store_dwordx2 v[192:193], v[16:17], off offset:288
	v_mov_b32_e32 v128, v248
	v_lshl_add_u64 v[190:191], s[98:99], 1, v[190:191]
	v_lshl_add_u64 v[192:193], s[98:99], 0, v[192:193]
	s_waitcnt vmcnt(8)
	s_waitcnt lgkmcnt(0)
	v_pk_fma_f32 v[14:15], v[14:15], v[144:145], v[234:235]
	v_pk_fma_f32 v[12:13], v[12:13], v[142:143], v[232:233]
	global_store_dwordx4 v[190:191], v[12:15], off
	v_pk_mul_f32 v[232:233], v[14:15], v[14:15]
	v_pk_mul_f32 v[234:235], v[12:13], v[12:13]
	v_pk_mul_f32 v[12:13], v[182:183], v[12:13]
	v_pk_mul_f32 v[14:15], v[184:185], v[14:15]
	v_add_f32_e32 v234, v234, v235
	v_add_f32_e32 v232, v232, v233
	v_add_f32_e32 v248, v234, v232
	v_cvt_pk_bf16_f32 v12, v12, v13
	v_cvt_pk_bf16_f32 v13, v14, v15
	global_store_dwordx2 v[192:193], v[12:13], off
	v_pk_fma_f32 v[10:11], v[10:11], v[140:141], v[238:239]
	v_pk_fma_f32 v[8:9], v[8:9], v[138:139], v[236:237]
	global_store_dwordx4 v[190:191], v[8:11], off offset:64
	v_pk_mul_f32 v[236:237], v[10:11], v[10:11]
	v_pk_mul_f32 v[238:239], v[8:9], v[8:9]
	v_pk_mul_f32 v[8:9], v[178:179], v[8:9]
	v_pk_mul_f32 v[10:11], v[180:181], v[10:11]
	v_add_f32_e32 v238, v238, v239
	v_add_f32_e32 v236, v236, v237
	v_add_f32_e32 v238, v238, v236
	v_add_f32_e32 v248, v248, v238
	v_cvt_pk_bf16_f32 v8, v8, v9
	v_cvt_pk_bf16_f32 v9, v10, v11
	global_store_dwordx2 v[192:193], v[8:9], off offset:32
	v_pk_fma_f32 v[6:7], v[6:7], v[136:137], v[242:243]
	v_pk_fma_f32 v[4:5], v[4:5], v[134:135], v[240:241]
	global_store_dwordx4 v[190:191], v[4:7], off offset:512
	v_pk_mul_f32 v[240:241], v[6:7], v[6:7]
	v_pk_mul_f32 v[242:243], v[4:5], v[4:5]
	v_pk_mul_f32 v[4:5], v[158:159], v[4:5]
	v_pk_mul_f32 v[6:7], v[160:161], v[6:7]
	v_add_f32_e32 v242, v242, v243
	v_add_f32_e32 v240, v240, v241
	v_add_f32_e32 v242, v242, v240
	v_add_f32_e32 v248, v248, v242
	v_cvt_pk_bf16_f32 v4, v4, v5
	v_cvt_pk_bf16_f32 v5, v6, v7
	global_store_dwordx2 v[192:193], v[4:5], off offset:256
	v_pk_fma_f32 v[2:3], v[2:3], v[132:133], v[246:247]
	v_pk_fma_f32 v[0:1], v[0:1], v[130:131], v[244:245]
	global_store_dwordx4 v[190:191], v[0:3], off offset:576
	v_pk_mul_f32 v[244:245], v[2:3], v[2:3]
	v_pk_mul_f32 v[246:247], v[0:1], v[0:1]
	v_pk_mul_f32 v[0:1], v[174:175], v[0:1]
	v_pk_mul_f32 v[2:3], v[176:177], v[2:3]
	v_add_f32_e32 v246, v246, v247
	v_add_f32_e32 v244, v244, v245
	v_add_f32_e32 v246, v246, v244
	v_add_f32_e32 v248, v248, v246
	v_cvt_pk_bf16_f32 v0, v0, v1
	v_cvt_pk_bf16_f32 v1, v2, v3
	global_store_dwordx2 v[192:193], v[0:1], off offset:288
	v_mov_b32_e32 v129, v248
	v_readlane_b32 s80, v252, 0
	v_readlane_b32 s81, v252, 1
	v_readlane_b32 s82, v254, 59
	v_lshl_add_u32 v250, s14, 8, v188
	v_ashrrev_i32_e32 v251, 31, v250
	v_lshlrev_b64 v[250:251], 6, v[250:251]
	s_lshl_b32 s98, s13, 2
	s_ashr_i32 s99, s98, 31
	v_lshl_add_u64 v[250:251], s[80:81], 0, v[250:251]
	v_lshl_add_u64 v[250:251], s[98:99], 2, v[250:251]
	s_lshl_b32 s24, s63, 2
	v_lshl_add_u64 v[250:251], v[250:251], 0, s[24:25]
	v_and_b32_e32 v249, 3, v81
	v_add_f32_dpp v122, v122, v122 quad_perm:[1,0,3,2] row_mask:0xf bank_mask:0xf
	v_add_f32_dpp v123, v123, v123 quad_perm:[1,0,3,2] row_mask:0xf bank_mask:0xf
	v_add_f32_dpp v124, v124, v124 quad_perm:[1,0,3,2] row_mask:0xf bank_mask:0xf
	v_add_f32_dpp v125, v125, v125 quad_perm:[1,0,3,2] row_mask:0xf bank_mask:0xf
; __device__ __forceinline__ unsigned cvt_pk_bf16(float lo, float hi) { unsigned r; asm volatile("v_cvt_pk_bf16_f32 %0, %1, %2" : "=v"(r) : "v"(lo), "v"(hi)); return r; }
;     __device__ __forceinline__ void operator()(const f32x4 (&acc)[2][2][4][2], const Unit& u, int wr, int wc, int fr_, int fq_, int) const {
;     ...
;                         if (lat) { const f32x4 s = *(const f32x4*)(src + off + bj * HALF + n * 16);
;                             const f32x4 o = s + g[bj][n] * acc[ai][bj][m][n];
;                             *(f32x4*)(dst + off + bj * HALF + n * 16) = o;
;                             if (emit) { const f32x4 q = o * o; ss += (q[0] + q[1]) + (q[2] + q[3]); const f32x4 xg = o * gm[bj][n];
;                                 u32x2 w; w.x = cvt_pk_bf16(xg[0], xg[1]); w.y = cvt_pk_bf16(xg[2], xg[3]); *(u32x2*)(XG + tb + off + bj * HALF + n * 16) = w; } }
;                         else *(f32x4*)(dst + off + bj * HALF + n * 16) = g[bj][n] * acc[ai][bj][m][n];
;                     }
;                 if (emit) { ss += __shfl_xor(ss, 16); ss += __shfl_xor(ss, 32); if (fq == 0) SS[(size_t)(u.pm * BM + ai * HALF + wr * 64 + m * 16 + fr) * 16 + u.pn * 4 + wc] = ss; }
	v_add_f32_dpp v126, v126, v126 quad_perm:[1,0,3,2] row_mask:0xf bank_mask:0xf
	v_add_f32_dpp v127, v127, v127 quad_perm:[1,0,3,2] row_mask:0xf bank_mask:0xf
	v_add_f32_dpp v128, v128, v128 quad_perm:[1,0,3,2] row_mask:0xf bank_mask:0xf
	v_add_f32_dpp v129, v129, v129 quad_perm:[1,0,3,2] row_mask:0xf bank_mask:0xf
	v_cmp_eq_u32_e64 s[44:45], 0, v249
	v_add_f32_dpp v122, v122, v122 quad_perm:[2,3,0,1] row_mask:0xf bank_mask:0xf
	v_add_f32_dpp v123, v123, v123 quad_perm:[2,3,0,1] row_mask:0xf bank_mask:0xf
	v_add_f32_dpp v124, v124, v124 quad_perm:[2,3,0,1] row_mask:0xf bank_mask:0xf
	v_add_f32_dpp v125, v125, v125 quad_perm:[2,3,0,1] row_mask:0xf bank_mask:0xf
	v_add_f32_dpp v126, v126, v126 quad_perm:[2,3,0,1] row_mask:0xf bank_mask:0xf
	v_add_f32_dpp v127, v127, v127 quad_perm:[2,3,0,1] row_mask:0xf bank_mask:0xf
	v_add_f32_dpp v128, v128, v128 quad_perm:[2,3,0,1] row_mask:0xf bank_mask:0xf
	v_add_f32_dpp v129, v129, v129 quad_perm:[2,3,0,1] row_mask:0xf bank_mask:0xf
	s_mov_b32 s98, 0x2000
	s_mov_b32 s99, 0
	s_and_saveexec_b64 s[38:39], s[44:45]
	global_store_dword v[250:251], v122, off
	global_store_dword v[250:251], v123, off offset:1024
	global_store_dword v[250:251], v124, off offset:2048
	global_store_dword v[250:251], v125, off offset:3072
	v_lshl_add_u64 v[250:251], s[98:99], 0, v[250:251]
	global_store_dword v[250:251], v126, off
	global_store_dword v[250:251], v127, off offset:1024
	global_store_dword v[250:251], v128, off offset:2048
	global_store_dword v[250:251], v129, off offset:3072
	s_or_b64 exec, exec, s[38:39]
	s_branch .LBB0_844
.LBB0_652:
	s_and_b64 vcc, exec, s[42:43]
	s_cbranch_vccz .Lres_ctx
	v_lshrrev_b32_e32 v189, 2, v81
	v_and_b32_e32 v249, 3, v81
	v_lshl_add_u32 v189, v212, 2, v189
	v_lshl_add_u32 v186, v249, 2, s24
	s_add_u32 s38, s21, s92
	s_addc_u32 s39, s77, s93
	v_ashrrev_i32_e32 v187, 31, v186
	v_lshlrev_b64 v[158:159], 2, v[186:187]
	v_lshl_add_u64 v[190:191], s[38:39], 0, v[158:159]
	global_load_dwordx4 v[142:145], v[190:191], off
	global_load_dwordx4 v[138:141], v[190:191], off offset:64
	global_load_dwordx4 v[134:137], v[190:191], off offset:512
	global_load_dwordx4 v[130:133], v[190:191], off offset:576
	s_mov_b32 s94, s14
	s_ashr_i32 s95, s94, 31
	s_lshl_b64 s[96:97], s[94:95], 20
	v_readlane_b32 s24, v252, 47
	s_add_u32 s92, s24, s96
	v_readlane_b32 s24, v252, 46
	s_addc_u32 s93, s24, s97
	s_add_u32 s96, s56, s96
	s_addc_u32 s97, s57, s97
	s_lshl_b32 s40, s3, 6
	s_lshl_b32 s41, s63, 10
	s_add_i32 s40, s40, s41
	s_add_i32 s40, s40, 0x20000
	v_bfe_u32 v250, v81, 1, 2
	v_xor_b32_e32 v250, v250, v212
	v_lshlrev_b32_e32 v250, 4, v250
	v_lshl_add_u32 v250, v81, 6, v250
	v_add_u32_e32 v250, s40, v250
	v_bfe_u32 v251, v189, 1, 2
	v_xor_b32_e32 v251, v251, v249
	v_lshlrev_b32_e32 v251, 4, v251
	v_lshl_add_u32 v251, v189, 6, v251
	v_add_u32_e32 v251, s40, v251
	ds_write_b128 v250, v[126:129]
	ds_read_b128 v[126:129], v251
	ds_write_b128 v250, v[122:125]
	ds_read_b128 v[122:125], v251
	ds_write_b128 v250, v[118:121]
	ds_read_b128 v[118:121], v251
	ds_write_b128 v250, v[114:117]
	ds_read_b128 v[114:117], v251
	v_add_u32_e32 v188, s3, v189
	v_ashrrev_i32_e32 v189, 31, v188
	v_lshlrev_b64 v[190:191], 10, v[188:189]
	v_lshl_add_u64 v[192:193], v[190:191], 0, v[186:187]
	v_lshlrev_b64 v[194:195], 2, v[192:193]
	v_lshl_add_u64 v[190:191], s[96:97], 0, v[194:195]
	v_lshl_add_u64 v[194:195], s[92:93], 0, v[194:195]
	global_load_dwordx4 v[216:219], v[194:195], off
	global_load_dwordx4 v[220:223], v[194:195], off offset:64
	global_load_dwordx4 v[224:227], v[194:195], off offset:512
	global_load_dwordx4 v[228:231], v[194:195], off offset:576
	s_mov_b32 s98, 0x8000
	s_mov_b32 s99, 0
	s_mov_b32 s96, 0x28000
	s_mov_b32 s97, 0
	v_mov_b32_e32 v151, v150
	s_waitcnt vmcnt(4)
	v_pk_mul_f32 v[142:143], v[150:151], v[142:143]
	v_pk_mul_f32 v[144:145], v[150:151], v[144:145]
	v_pk_mul_f32 v[138:139], v[150:151], v[138:139]
	v_pk_mul_f32 v[140:141], v[150:151], v[140:141]
	v_pk_mul_f32 v[134:135], v[150:151], v[134:135]
	v_pk_mul_f32 v[136:137], v[150:151], v[136:137]
	v_pk_mul_f32 v[130:131], v[150:151], v[130:131]
	v_pk_mul_f32 v[132:133], v[150:151], v[132:133]
	v_lshl_add_u64 v[194:195], s[98:99], 1, v[194:195]
	global_load_dwordx4 v[232:235], v[194:195], off
	global_load_dwordx4 v[236:239], v[194:195], off offset:64
	global_load_dwordx4 v[240:243], v[194:195], off offset:512
	global_load_dwordx4 v[244:247], v[194:195], off offset:576
	s_waitcnt lgkmcnt(0)
	ds_write_b128 v250, v[110:113]
	ds_read_b128 v[110:113], v251
	ds_write_b128 v250, v[106:109]
	ds_read_b128 v[106:109], v251
	ds_write_b128 v250, v[102:105]
	ds_read_b128 v[102:105], v251
	ds_write_b128 v250, v[98:101]
	ds_read_b128 v[98:101], v251
	s_waitcnt vmcnt(4)
	v_pk_fma_f32 v[128:129], v[128:129], v[144:145], v[218:219]
	v_pk_fma_f32 v[126:127], v[126:127], v[142:143], v[216:217]
	global_store_dwordx4 v[190:191], v[126:129], off
	v_pk_fma_f32 v[124:125], v[124:125], v[140:141], v[222:223]
	v_pk_fma_f32 v[122:123], v[122:123], v[138:139], v[220:221]
	global_store_dwordx4 v[190:191], v[122:125], off offset:64
	v_pk_fma_f32 v[120:121], v[120:121], v[136:137], v[226:227]
	v_pk_fma_f32 v[118:119], v[118:119], v[134:135], v[224:225]
	global_store_dwordx4 v[190:191], v[118:121], off offset:512
	v_pk_fma_f32 v[116:117], v[116:117], v[132:133], v[230:231]
	v_pk_fma_f32 v[114:115], v[114:115], v[130:131], v[228:229]
	global_store_dwordx4 v[190:191], v[114:117], off offset:576
	v_lshl_add_u64 v[190:191], s[98:99], 1, v[190:191]
	v_lshl_add_u64 v[194:195], s[98:99], 1, v[194:195]
	global_load_dwordx4 v[216:219], v[194:195], off
	global_load_dwordx4 v[220:223], v[194:195], off offset:64
	global_load_dwordx4 v[224:227], v[194:195], off offset:512
	global_load_dwordx4 v[228:231], v[194:195], off offset:576
	ds_write_b128 v250, v[94:97]
	ds_read_b128 v[94:97], v251
	ds_write_b128 v250, v[90:93]
	ds_read_b128 v[90:93], v251
	ds_write_b128 v250, v[86:89]
	ds_read_b128 v[86:89], v251
	ds_write_b128 v250, v[82:85]
	ds_read_b128 v[82:85], v251
	s_waitcnt vmcnt(8)
;     __device__ __forceinline__ void operator()(const f32x4 (&acc)[2][2][4][2], const Unit& u, int wr, int wc, int fr_, int fq_, int) const {
;     ...
;         for (int ai = 0; ai < 2; ++ai)
; #pragma unroll
;             for (int m = 0; m < 4; ++m) { const size_t off = (size_t)(ai * HALF + wr * 64 + m * 16 + fr) * E_DM + col0; float ss = 0.f;
; #pragma unroll
;                 for (int bj = 0; bj < 2; ++bj)
; #pragma unroll
;                     for (int n = 0; n < 2; ++n) {
;                         if (lat) { const f32x4 s = *(const f32x4*)(src + off + bj * HALF + n * 16);
;                             const f32x4 o = s + g[bj][n] * acc[ai][bj][m][n];
;                             *(f32x4*)(dst + off + bj * HALF + n * 16) = o;
	s_waitcnt lgkmcnt(8)
	v_pk_fma_f32 v[112:113], v[112:113], v[144:145], v[234:235]
	v_pk_fma_f32 v[110:111], v[110:111], v[142:143], v[232:233]
	global_store_dwordx4 v[190:191], v[110:113], off
	v_pk_fma_f32 v[108:109], v[108:109], v[140:141], v[238:239]
	v_pk_fma_f32 v[106:107], v[106:107], v[138:139], v[236:237]
	global_store_dwordx4 v[190:191], v[106:109], off offset:64
	v_pk_fma_f32 v[104:105], v[104:105], v[136:137], v[242:243]
	v_pk_fma_f32 v[102:103], v[102:103], v[134:135], v[240:241]
	global_store_dwordx4 v[190:191], v[102:105], off offset:512
	v_pk_fma_f32 v[100:101], v[100:101], v[132:133], v[246:247]
	v_pk_fma_f32 v[98:99], v[98:99], v[130:131], v[244:245]
	global_store_dwordx4 v[190:191], v[98:101], off offset:576
	v_lshl_add_u64 v[190:191], s[98:99], 1, v[190:191]
	v_lshl_add_u64 v[194:195], s[98:99], 1, v[194:195]
	global_load_dwordx4 v[232:235], v[194:195], off
	global_load_dwordx4 v[236:239], v[194:195], off offset:64
	global_load_dwordx4 v[240:243], v[194:195], off offset:512
	global_load_dwordx4 v[244:247], v[194:195], off offset:576
	ds_write_b128 v250, v[76:79]
	ds_read_b128 v[76:79], v251
	ds_write_b128 v250, v[72:75]
	ds_read_b128 v[72:75], v251
	ds_write_b128 v250, v[68:71]
	ds_read_b128 v[68:71], v251
	ds_write_b128 v250, v[64:67]
	ds_read_b128 v[64:67], v251
	s_waitcnt vmcnt(8)
	s_waitcnt lgkmcnt(8)
	v_pk_fma_f32 v[96:97], v[96:97], v[144:145], v[218:219]
	v_pk_fma_f32 v[94:95], v[94:95], v[142:143], v[216:217]
	global_store_dwordx4 v[190:191], v[94:97], off
	v_pk_fma_f32 v[92:93], v[92:93], v[140:141], v[222:223]
	v_pk_fma_f32 v[90:91], v[90:91], v[138:139], v[220:221]
	global_store_dwordx4 v[190:191], v[90:93], off offset:64
	v_pk_fma_f32 v[88:89], v[88:89], v[136:137], v[226:227]
	v_pk_fma_f32 v[86:87], v[86:87], v[134:135], v[224:225]
	global_store_dwordx4 v[190:191], v[86:89], off offset:512
	v_pk_fma_f32 v[84:85], v[84:85], v[132:133], v[230:231]
	v_pk_fma_f32 v[82:83], v[82:83], v[130:131], v[228:229]
	global_store_dwordx4 v[190:191], v[82:85], off offset:576
	v_lshl_add_u64 v[190:191], s[98:99], 1, v[190:191]
	v_lshl_add_u64 v[194:195], s[96:97], 1, v[194:195]
	global_load_dwordx4 v[216:219], v[194:195], off
	global_load_dwordx4 v[220:223], v[194:195], off offset:64
	global_load_dwordx4 v[224:227], v[194:195], off offset:512
	global_load_dwordx4 v[228:231], v[194:195], off offset:576
	ds_write_b128 v250, v[60:63]
	ds_read_b128 v[60:63], v251
	ds_write_b128 v250, v[56:59]
	ds_read_b128 v[56:59], v251
	ds_write_b128 v250, v[52:55]
	ds_read_b128 v[52:55], v251
	ds_write_b128 v250, v[48:51]
	ds_read_b128 v[48:51], v251
	s_waitcnt vmcnt(8)
	s_waitcnt lgkmcnt(8)
	v_pk_fma_f32 v[78:79], v[78:79], v[144:145], v[234:235]
	v_pk_fma_f32 v[76:77], v[76:77], v[142:143], v[232:233]
	global_store_dwordx4 v[190:191], v[76:79], off
	v_pk_fma_f32 v[74:75], v[74:75], v[140:141], v[238:239]
	v_pk_fma_f32 v[72:73], v[72:73], v[138:139], v[236:237]
	global_store_dwordx4 v[190:191], v[72:75], off offset:64
	v_pk_fma_f32 v[70:71], v[70:71], v[136:137], v[242:243]
	v_pk_fma_f32 v[68:69], v[68:69], v[134:135], v[240:241]
	global_store_dwordx4 v[190:191], v[68:71], off offset:512
	v_pk_fma_f32 v[66:67], v[66:67], v[132:133], v[246:247]
	v_pk_fma_f32 v[64:65], v[64:65], v[130:131], v[244:245]
	global_store_dwordx4 v[190:191], v[64:67], off offset:576
	v_lshl_add_u64 v[190:191], s[96:97], 1, v[190:191]
	v_lshl_add_u64 v[194:195], s[98:99], 1, v[194:195]
	global_load_dwordx4 v[232:235], v[194:195], off
	global_load_dwordx4 v[236:239], v[194:195], off offset:64
	global_load_dwordx4 v[240:243], v[194:195], off offset:512
	global_load_dwordx4 v[244:247], v[194:195], off offset:576
	ds_write_b128 v250, v[44:47]
	ds_read_b128 v[44:47], v251
	ds_write_b128 v250, v[40:43]
	ds_read_b128 v[40:43], v251
	ds_write_b128 v250, v[36:39]
	ds_read_b128 v[36:39], v251
	ds_write_b128 v250, v[32:35]
	ds_read_b128 v[32:35], v251
	s_waitcnt vmcnt(8)
	s_waitcnt lgkmcnt(8)
	v_pk_fma_f32 v[62:63], v[62:63], v[144:145], v[218:219]
	v_pk_fma_f32 v[60:61], v[60:61], v[142:143], v[216:217]
	global_store_dwordx4 v[190:191], v[60:63], off
	v_pk_fma_f32 v[58:59], v[58:59], v[140:141], v[222:223]
	v_pk_fma_f32 v[56:57], v[56:57], v[138:139], v[220:221]
	global_store_dwordx4 v[190:191], v[56:59], off offset:64
	v_pk_fma_f32 v[54:55], v[54:55], v[136:137], v[226:227]
	v_pk_fma_f32 v[52:53], v[52:53], v[134:135], v[224:225]
	global_store_dwordx4 v[190:191], v[52:55], off offset:512
	v_pk_fma_f32 v[50:51], v[50:51], v[132:133], v[230:231]
	v_pk_fma_f32 v[48:49], v[48:49], v[130:131], v[228:229]
	global_store_dwordx4 v[190:191], v[48:51], off offset:576
	v_lshl_add_u64 v[190:191], s[98:99], 1, v[190:191]
	v_lshl_add_u64 v[194:195], s[98:99], 1, v[194:195]
	global_load_dwordx4 v[216:219], v[194:195], off
	global_load_dwordx4 v[220:223], v[194:195], off offset:64
	global_load_dwordx4 v[224:227], v[194:195], off offset:512
	global_load_dwordx4 v[228:231], v[194:195], off offset:576
	ds_write_b128 v250, v[28:31]
	ds_read_b128 v[28:31], v251
	ds_write_b128 v250, v[24:27]
	ds_read_b128 v[24:27], v251
	ds_write_b128 v250, v[20:23]
	ds_read_b128 v[20:23], v251
	ds_write_b128 v250, v[16:19]
	ds_read_b128 v[16:19], v251
	s_waitcnt vmcnt(8)
	s_waitcnt lgkmcnt(8)
; __device__ __forceinline__ unsigned cvt_pk_bf16(float lo, float hi) { unsigned r; asm volatile("v_cvt_pk_bf16_f32 %0, %1, %2" : "=v"(r) : "v"(lo), "v"(hi)); return r; }
;     __device__ __forceinline__ void operator()(const f32x4 (&acc)[2][2][4][2], const Unit& u, int wr, int wc, int fr_, int fq_, int) const {
;     ...
;         const size_t tb = lat ? (size_t)u.pm * BM * E_DM : (size_t)(u.pm - 128) * BM * E_DM;
;         const float* src = src_lat + tb; float* dst = (lat ? dst_lat : dst_ctx + (size_t)(u.kt0 >> 2) * (1024 * E_DM)) + tb;
;         const int col0 = u.pn * BM + wc * 32 + 4 * fq;
;     ...
;         for (int ai = 0; ai < 2; ++ai)
; #pragma unroll
;             for (int m = 0; m < 4; ++m) { const size_t off = (size_t)(ai * HALF + wr * 64 + m * 16 + fr) * E_DM + col0; float ss = 0.f;
; #pragma unroll
;                 for (int bj = 0; bj < 2; ++bj)
; #pragma unroll
;                     for (int n = 0; n < 2; ++n) {
;                         if (lat) { const f32x4 s = *(const f32x4*)(src + off + bj * HALF + n * 16);
;                             const f32x4 o = s + g[bj][n] * acc[ai][bj][m][n];
;                             *(f32x4*)(dst + off + bj * HALF + n * 16) = o;
;                             if (emit) { const f32x4 q = o * o; ss += (q[0] + q[1]) + (q[2] + q[3]); const f32x4 xg = o * gm[bj][n];
;                                 u32x2 w; w.x = cvt_pk_bf16(xg[0], xg[1]); w.y = cvt_pk_bf16(xg[2], xg[3]); *(u32x2*)(XG + tb + off + bj * HALF + n * 16) = w; } }
;                         else *(f32x4*)(dst + off + bj * HALF + n * 16) = g[bj][n] * acc[ai][bj][m][n];
	v_pk_fma_f32 v[46:47], v[46:47], v[144:145], v[234:235]
	v_pk_fma_f32 v[44:45], v[44:45], v[142:143], v[232:233]
	global_store_dwordx4 v[190:191], v[44:47], off
	v_pk_fma_f32 v[42:43], v[42:43], v[140:141], v[238:239]
	v_pk_fma_f32 v[40:41], v[40:41], v[138:139], v[236:237]
	global_store_dwordx4 v[190:191], v[40:43], off offset:64
	v_pk_fma_f32 v[38:39], v[38:39], v[136:137], v[242:243]
	v_pk_fma_f32 v[36:37], v[36:37], v[134:135], v[240:241]
	global_store_dwordx4 v[190:191], v[36:39], off offset:512
	v_pk_fma_f32 v[34:35], v[34:35], v[132:133], v[246:247]
	v_pk_fma_f32 v[32:33], v[32:33], v[130:131], v[244:245]
	global_store_dwordx4 v[190:191], v[32:35], off offset:576
	v_lshl_add_u64 v[190:191], s[98:99], 1, v[190:191]
	v_lshl_add_u64 v[194:195], s[98:99], 1, v[194:195]
	global_load_dwordx4 v[232:235], v[194:195], off
	global_load_dwordx4 v[236:239], v[194:195], off offset:64
	global_load_dwordx4 v[240:243], v[194:195], off offset:512
	global_load_dwordx4 v[244:247], v[194:195], off offset:576
	ds_write_b128 v250, v[12:15]
	ds_read_b128 v[12:15], v251
	ds_write_b128 v250, v[8:11]
	ds_read_b128 v[8:11], v251
	ds_write_b128 v250, v[4:7]
	ds_read_b128 v[4:7], v251
	ds_write_b128 v250, v[0:3]
	ds_read_b128 v[0:3], v251
	s_waitcnt vmcnt(8)
	s_waitcnt lgkmcnt(8)
	v_pk_fma_f32 v[30:31], v[30:31], v[144:145], v[218:219]
	v_pk_fma_f32 v[28:29], v[28:29], v[142:143], v[216:217]
	global_store_dwordx4 v[190:191], v[28:31], off
	v_pk_fma_f32 v[26:27], v[26:27], v[140:141], v[222:223]
	v_pk_fma_f32 v[24:25], v[24:25], v[138:139], v[220:221]
	global_store_dwordx4 v[190:191], v[24:27], off offset:64
	v_pk_fma_f32 v[22:23], v[22:23], v[136:137], v[226:227]
	v_pk_fma_f32 v[20:21], v[20:21], v[134:135], v[224:225]
	global_store_dwordx4 v[190:191], v[20:23], off offset:512
	v_pk_fma_f32 v[18:19], v[18:19], v[132:133], v[230:231]
	v_pk_fma_f32 v[16:17], v[16:17], v[130:131], v[228:229]
	global_store_dwordx4 v[190:191], v[16:19], off offset:576
	v_lshl_add_u64 v[190:191], s[98:99], 1, v[190:191]
	s_waitcnt vmcnt(4)
	s_waitcnt lgkmcnt(0)
	v_pk_fma_f32 v[14:15], v[14:15], v[144:145], v[234:235]
	v_pk_fma_f32 v[12:13], v[12:13], v[142:143], v[232:233]
	global_store_dwordx4 v[190:191], v[12:15], off
	v_pk_fma_f32 v[10:11], v[10:11], v[140:141], v[238:239]
	v_pk_fma_f32 v[8:9], v[8:9], v[138:139], v[236:237]
	global_store_dwordx4 v[190:191], v[8:11], off offset:64
	v_pk_fma_f32 v[6:7], v[6:7], v[136:137], v[242:243]
	v_pk_fma_f32 v[4:5], v[4:5], v[134:135], v[240:241]
	global_store_dwordx4 v[190:191], v[4:7], off offset:512
	v_pk_fma_f32 v[2:3], v[2:3], v[132:133], v[246:247]
	v_pk_fma_f32 v[0:1], v[0:1], v[130:131], v[244:245]
	global_store_dwordx4 v[190:191], v[0:3], off offset:576
	v_readlane_b32 s80, v252, 0
	v_readlane_b32 s81, v252, 1
	v_readlane_b32 s82, v254, 59
	s_branch .LBB0_844
.Lres_ctx:
	v_lshrrev_b32_e32 v189, 2, v81
	v_and_b32_e32 v249, 3, v81
	v_lshl_add_u32 v189, v212, 2, v189
	v_lshl_add_u32 v186, v249, 2, s24
	s_add_u32 s38, s21, s92
	s_addc_u32 s39, s77, s93
	v_ashrrev_i32_e32 v187, 31, v186
	v_lshlrev_b64 v[158:159], 2, v[186:187]
	v_lshl_add_u64 v[190:191], s[38:39], 0, v[158:159]
	global_load_dwordx4 v[142:145], v[190:191], off
	global_load_dwordx4 v[138:141], v[190:191], off offset:64
	global_load_dwordx4 v[134:137], v[190:191], off offset:512
	global_load_dwordx4 v[130:133], v[190:191], off offset:576
	s_add_i32 s94, s14, 0xffffff80
	s_ashr_i32 s95, s94, 31
	s_lshl_b64 s[96:97], s[94:95], 20
	s_ashr_i32 s40, s40, 2
	s_ashr_i32 s41, s40, 31
	s_lshl_b64 s[40:41], s[40:41], 22
	s_add_u32 s40, s86, s40
	s_addc_u32 s41, s87, s41
	s_add_u32 s96, s40, s96
	s_addc_u32 s97, s41, s97
	s_lshl_b32 s40, s3, 6
	s_lshl_b32 s41, s63, 10
	s_add_i32 s40, s40, s41
	s_add_i32 s40, s40, 0x20000
	v_bfe_u32 v250, v81, 1, 2
	v_xor_b32_e32 v250, v250, v212
	v_lshlrev_b32_e32 v250, 4, v250
	v_lshl_add_u32 v250, v81, 6, v250
	v_add_u32_e32 v250, s40, v250
	v_bfe_u32 v251, v189, 1, 2
	v_xor_b32_e32 v251, v251, v249
	v_lshlrev_b32_e32 v251, 4, v251
	v_lshl_add_u32 v251, v189, 6, v251
	v_add_u32_e32 v251, s40, v251
	ds_write_b128 v250, v[126:129]
	ds_read_b128 v[126:129], v251
	ds_write_b128 v250, v[122:125]
	ds_read_b128 v[122:125], v251
	ds_write_b128 v250, v[118:121]
	ds_read_b128 v[118:121], v251
	ds_write_b128 v250, v[114:117]
	ds_read_b128 v[114:117], v251
	v_add_u32_e32 v188, s3, v189
	v_ashrrev_i32_e32 v189, 31, v188
	v_lshlrev_b64 v[190:191], 10, v[188:189]
	v_lshl_add_u64 v[192:193], v[190:191], 0, v[186:187]
	v_lshlrev_b64 v[194:195], 2, v[192:193]
	v_lshl_add_u64 v[190:191], s[96:97], 0, v[194:195]
	s_mov_b32 s98, 0x8000
	s_mov_b32 s99, 0
	s_mov_b32 s96, 0x28000
	s_mov_b32 s97, 0
	v_mov_b32_e32 v151, v150
	s_waitcnt vmcnt(0)
	v_pk_mul_f32 v[142:143], v[150:151], v[142:143]
	v_pk_mul_f32 v[144:145], v[150:151], v[144:145]
	v_pk_mul_f32 v[138:139], v[150:151], v[138:139]
	v_pk_mul_f32 v[140:141], v[150:151], v[140:141]
	v_pk_mul_f32 v[134:135], v[150:151], v[134:135]
	v_pk_mul_f32 v[136:137], v[150:151], v[136:137]
	v_pk_mul_f32 v[130:131], v[150:151], v[130:131]
	v_pk_mul_f32 v[132:133], v[150:151], v[132:133]
	s_waitcnt lgkmcnt(0)
; __device__ __forceinline__ unsigned cvt_pk_bf16(float lo, float hi) { unsigned r; asm volatile("v_cvt_pk_bf16_f32 %0, %1, %2" : "=v"(r) : "v"(lo), "v"(hi)); return r; }
;     __device__ __forceinline__ void operator()(const f32x4 (&acc)[2][2][4][2], const Unit& u, int wr, int wc, int fr_, int fq_, int) const {
;     ...
;         for (int ai = 0; ai < 2; ++ai)
; #pragma unroll
;             for (int m = 0; m < 4; ++m) { const size_t off = (size_t)(ai * HALF + wr * 64 + m * 16 + fr) * E_DM + col0; float ss = 0.f;
; #pragma unroll
;                 for (int bj = 0; bj < 2; ++bj)
; #pragma unroll
;                     for (int n = 0; n < 2; ++n) {
;                         if (lat) { const f32x4 s = *(const f32x4*)(src + off + bj * HALF + n * 16);
;                             const f32x4 o = s + g[bj][n] * acc[ai][bj][m][n];
;                             *(f32x4*)(dst + off + bj * HALF + n * 16) = o;
;                             if (emit) { const f32x4 q = o * o; ss += (q[0] + q[1]) + (q[2] + q[3]); const f32x4 xg = o * gm[bj][n];
;                                 u32x2 w; w.x = cvt_pk_bf16(xg[0], xg[1]); w.y = cvt_pk_bf16(xg[2], xg[3]); *(u32x2*)(XG + tb + off + bj * HALF + n * 16) = w; } }
;                         else *(f32x4*)(dst + off + bj * HALF + n * 16) = g[bj][n] * acc[ai][bj][m][n];
	ds_write_b128 v250, v[110:113]
	ds_read_b128 v[110:113], v251
	ds_write_b128 v250, v[106:109]
	ds_read_b128 v[106:109], v251
	ds_write_b128 v250, v[102:105]
	ds_read_b128 v[102:105], v251
	ds_write_b128 v250, v[98:101]
	ds_read_b128 v[98:101], v251
	v_pk_mul_f32 v[128:129], v[128:129], v[144:145]
	v_pk_mul_f32 v[126:127], v[126:127], v[142:143]
	global_store_dwordx4 v[190:191], v[126:129], off
	v_pk_mul_f32 v[124:125], v[124:125], v[140:141]
	v_pk_mul_f32 v[122:123], v[122:123], v[138:139]
	global_store_dwordx4 v[190:191], v[122:125], off offset:64
	v_pk_mul_f32 v[120:121], v[120:121], v[136:137]
	v_pk_mul_f32 v[118:119], v[118:119], v[134:135]
	global_store_dwordx4 v[190:191], v[118:121], off offset:512
	v_pk_mul_f32 v[116:117], v[116:117], v[132:133]
	v_pk_mul_f32 v[114:115], v[114:115], v[130:131]
	global_store_dwordx4 v[190:191], v[114:117], off offset:576
	v_lshl_add_u64 v[190:191], s[98:99], 1, v[190:191]
	ds_write_b128 v250, v[94:97]
	ds_read_b128 v[94:97], v251
	ds_write_b128 v250, v[90:93]
	ds_read_b128 v[90:93], v251
	ds_write_b128 v250, v[86:89]
	ds_read_b128 v[86:89], v251
	ds_write_b128 v250, v[82:85]
	ds_read_b128 v[82:85], v251
	s_waitcnt lgkmcnt(8)
	v_pk_mul_f32 v[112:113], v[112:113], v[144:145]
	v_pk_mul_f32 v[110:111], v[110:111], v[142:143]
	global_store_dwordx4 v[190:191], v[110:113], off
	v_pk_mul_f32 v[108:109], v[108:109], v[140:141]
	v_pk_mul_f32 v[106:107], v[106:107], v[138:139]
	global_store_dwordx4 v[190:191], v[106:109], off offset:64
	v_pk_mul_f32 v[104:105], v[104:105], v[136:137]
	v_pk_mul_f32 v[102:103], v[102:103], v[134:135]
	global_store_dwordx4 v[190:191], v[102:105], off offset:512
	v_pk_mul_f32 v[100:101], v[100:101], v[132:133]
	v_pk_mul_f32 v[98:99], v[98:99], v[130:131]
	global_store_dwordx4 v[190:191], v[98:101], off offset:576
	v_lshl_add_u64 v[190:191], s[98:99], 1, v[190:191]
	ds_write_b128 v250, v[76:79]
	ds_read_b128 v[76:79], v251
	ds_write_b128 v250, v[72:75]
	ds_read_b128 v[72:75], v251
	ds_write_b128 v250, v[68:71]
	ds_read_b128 v[68:71], v251
	ds_write_b128 v250, v[64:67]
	ds_read_b128 v[64:67], v251
	s_waitcnt lgkmcnt(8)
	v_pk_mul_f32 v[96:97], v[96:97], v[144:145]
	v_pk_mul_f32 v[94:95], v[94:95], v[142:143]
	global_store_dwordx4 v[190:191], v[94:97], off
	v_pk_mul_f32 v[92:93], v[92:93], v[140:141]
	v_pk_mul_f32 v[90:91], v[90:91], v[138:139]
	global_store_dwordx4 v[190:191], v[90:93], off offset:64
	v_pk_mul_f32 v[88:89], v[88:89], v[136:137]
	v_pk_mul_f32 v[86:87], v[86:87], v[134:135]
	global_store_dwordx4 v[190:191], v[86:89], off offset:512
	v_pk_mul_f32 v[84:85], v[84:85], v[132:133]
	v_pk_mul_f32 v[82:83], v[82:83], v[130:131]
	global_store_dwordx4 v[190:191], v[82:85], off offset:576
	v_lshl_add_u64 v[190:191], s[98:99], 1, v[190:191]
	ds_write_b128 v250, v[60:63]
	ds_read_b128 v[60:63], v251
	ds_write_b128 v250, v[56:59]
	ds_read_b128 v[56:59], v251
	ds_write_b128 v250, v[52:55]
	ds_read_b128 v[52:55], v251
	ds_write_b128 v250, v[48:51]
	ds_read_b128 v[48:51], v251
	s_waitcnt lgkmcnt(8)
	v_pk_mul_f32 v[78:79], v[78:79], v[144:145]
	v_pk_mul_f32 v[76:77], v[76:77], v[142:143]
	global_store_dwordx4 v[190:191], v[76:79], off
	v_pk_mul_f32 v[74:75], v[74:75], v[140:141]
	v_pk_mul_f32 v[72:73], v[72:73], v[138:139]
	global_store_dwordx4 v[190:191], v[72:75], off offset:64
	v_pk_mul_f32 v[70:71], v[70:71], v[136:137]
	v_pk_mul_f32 v[68:69], v[68:69], v[134:135]
	global_store_dwordx4 v[190:191], v[68:71], off offset:512
	v_pk_mul_f32 v[66:67], v[66:67], v[132:133]
	v_pk_mul_f32 v[64:65], v[64:65], v[130:131]
	global_store_dwordx4 v[190:191], v[64:67], off offset:576
	v_lshl_add_u64 v[190:191], s[96:97], 1, v[190:191]
	ds_write_b128 v250, v[44:47]
	ds_read_b128 v[44:47], v251
	ds_write_b128 v250, v[40:43]
	ds_read_b128 v[40:43], v251
	ds_write_b128 v250, v[36:39]
	ds_read_b128 v[36:39], v251
	ds_write_b128 v250, v[32:35]
	ds_read_b128 v[32:35], v251
	s_waitcnt lgkmcnt(8)
	v_pk_mul_f32 v[62:63], v[62:63], v[144:145]
	v_pk_mul_f32 v[60:61], v[60:61], v[142:143]
	global_store_dwordx4 v[190:191], v[60:63], off
	v_pk_mul_f32 v[58:59], v[58:59], v[140:141]
	v_pk_mul_f32 v[56:57], v[56:57], v[138:139]
	global_store_dwordx4 v[190:191], v[56:59], off offset:64
	v_pk_mul_f32 v[54:55], v[54:55], v[136:137]
	v_pk_mul_f32 v[52:53], v[52:53], v[134:135]
	global_store_dwordx4 v[190:191], v[52:55], off offset:512
	v_pk_mul_f32 v[50:51], v[50:51], v[132:133]
	v_pk_mul_f32 v[48:49], v[48:49], v[130:131]
	global_store_dwordx4 v[190:191], v[48:51], off offset:576
	v_lshl_add_u64 v[190:191], s[98:99], 1, v[190:191]
	ds_write_b128 v250, v[28:31]
	ds_read_b128 v[28:31], v251
	ds_write_b128 v250, v[24:27]
	ds_read_b128 v[24:27], v251
	ds_write_b128 v250, v[20:23]
	ds_read_b128 v[20:23], v251
	ds_write_b128 v250, v[16:19]
	ds_read_b128 v[16:19], v251
	s_waitcnt lgkmcnt(8)
	v_pk_mul_f32 v[46:47], v[46:47], v[144:145]
	v_pk_mul_f32 v[44:45], v[44:45], v[142:143]
	global_store_dwordx4 v[190:191], v[44:47], off
	v_pk_mul_f32 v[42:43], v[42:43], v[140:141]
	v_pk_mul_f32 v[40:41], v[40:41], v[138:139]
	global_store_dwordx4 v[190:191], v[40:43], off offset:64
	v_pk_mul_f32 v[38:39], v[38:39], v[136:137]
	v_pk_mul_f32 v[36:37], v[36:37], v[134:135]
	global_store_dwordx4 v[190:191], v[36:39], off offset:512
	v_pk_mul_f32 v[34:35], v[34:35], v[132:133]
	v_pk_mul_f32 v[32:33], v[32:33], v[130:131]
	global_store_dwordx4 v[190:191], v[32:35], off offset:576
	v_lshl_add_u64 v[190:191], s[98:99], 1, v[190:191]
	ds_write_b128 v250, v[12:15]
	ds_read_b128 v[12:15], v251
	ds_write_b128 v250, v[8:11]
	ds_read_b128 v[8:11], v251
	ds_write_b128 v250, v[4:7]
	ds_read_b128 v[4:7], v251
	ds_write_b128 v250, v[0:3]
	ds_read_b128 v[0:3], v251
	s_waitcnt lgkmcnt(8)
	v_pk_mul_f32 v[30:31], v[30:31], v[144:145]
	v_pk_mul_f32 v[28:29], v[28:29], v[142:143]
	global_store_dwordx4 v[190:191], v[28:31], off
	v_pk_mul_f32 v[26:27], v[26:27], v[140:141]
	v_pk_mul_f32 v[24:25], v[24:25], v[138:139]
	global_store_dwordx4 v[190:191], v[24:27], off offset:64
	v_pk_mul_f32 v[22:23], v[22:23], v[136:137]
	v_pk_mul_f32 v[20:21], v[20:21], v[134:135]
	global_store_dwordx4 v[190:191], v[20:23], off offset:512
	v_pk_mul_f32 v[18:19], v[18:19], v[132:133]
	v_pk_mul_f32 v[16:17], v[16:17], v[130:131]
	global_store_dwordx4 v[190:191], v[16:19], off offset:576
	v_lshl_add_u64 v[190:191], s[98:99], 1, v[190:191]
	s_waitcnt lgkmcnt(0)
	v_pk_mul_f32 v[14:15], v[14:15], v[144:145]
	v_pk_mul_f32 v[12:13], v[12:13], v[142:143]
	global_store_dwordx4 v[190:191], v[12:15], off
	v_pk_mul_f32 v[10:11], v[10:11], v[140:141]
	v_pk_mul_f32 v[8:9], v[8:9], v[138:139]
	global_store_dwordx4 v[190:191], v[8:11], off offset:64
	v_pk_mul_f32 v[6:7], v[6:7], v[136:137]
	v_pk_mul_f32 v[4:5], v[4:5], v[134:135]
	global_store_dwordx4 v[190:191], v[4:7], off offset:512
	v_pk_mul_f32 v[2:3], v[2:3], v[132:133]
	v_pk_mul_f32 v[0:1], v[0:1], v[130:131]
	global_store_dwordx4 v[190:191], v[0:3], off offset:576
	v_readlane_b32 s80, v252, 0
	v_readlane_b32 s81, v252, 1
	v_readlane_b32 s82, v254, 59
	s_branch .LBB0_844
